# strategy 6: phase C K/V chunk tiles in LDS unpadded with XOR-swizzled 16-byte chunks (conflict-free ds_read_b128 fragment reads), writers and readers changed together
# speedup vs baseline: 1.0060x; 1.0060x over previous
; DI int my_tid() { int t = threadIdx.x; asm volatile("" : "+v"(t)); return t; }
; DI void nsa_ldsfrag(KVFrag& f, const unsigned char* slot, int qi, int quad) {
;   const int krow = 8 * (qi >> 2) + (qi & 3);
; #pragma unroll
;   for (int a = 0; a < 2; ++a) { const unsigned char* kp = slot + (krow + 4 * a) * NSA_KROW + quad * 16; f.k[a][0] = mk8(*(const u32x4*)kp); f.k[a][1] = mk8(*(const u32x4*)(kp + 64)); }
; #pragma unroll
;   for (int dt = 0; dt < 4; ++dt) f.v[dt] = mk8(*(const u32x4*)(slot + 32 * NSA_KROW + (dt * 16 + qi) * NSA_VROW + quad * 16));
; }
; template <int MODE>
; DI void nsa_branch(const bf16_t* __restrict__ Kb, const bf16_t* __restrict__ Vtb, unsigned char* lds, int nb, int t, int cur, unsigned selmask, unsigned umall,
;                    const bf16x8 (&qf)[4][2], f32x4 (&O)[4][4], float (&m)[4], float (&l)[4], bool online) {
;   const int tid = my_tid(), lane = tid & 63, qi = lane & 15, quad = lane >> 4;
;   const int* blist = (const int*)(lds + NSA_BLIST);
;   const bool isv = tid >= 256;
;   const int t2 = tid & 255;
;   const bf16_t* gsrc = isv ? Vtb + (t2 >> 2) * 32 + (t2 & 3) * 8 : Kb + (long)(t2 >> 3) * 64 + (t2 & 7) * 8;
;   const long gmul = 64;
;   const int ldst = isv ? 32 * NSA_KROW + (t2 >> 2) * NSA_VROW + (t2 & 3) * 16 : (t2 >> 3) * NSA_KROW + (t2 & 7) * 16;
;   unsigned char* slot0 = lds + NSA_SLOT0; unsigned char* slot1 = slot0 + NSA_SLOT;
;   const int N = 2 * nb;
;   auto kbof = [&](int n) { return blist[n >> 1] * 64 + (n & 1) * 32; };
;   u32x4 ra = *(const u32x4*)(gsrc + (long)kbof(0) * gmul), rb = *(const u32x4*)(gsrc + (long)kbof(1) * gmul);
;   *(u32x4*)(slot0 + ldst) = ra;
;   __syncthreads();
.LBB0_719:
	s_or_b64 exec, exec, s[0:1]
	v_mov_b32_e32 v2, v210
	s_movk_i32 s0, 0xff
	s_waitcnt lgkmcnt(0)
	s_barrier
	s_nop 0
	v_cmp_lt_i32_e32 vcc, s0, v2
	s_movk_i32 s0, 0x100
	v_cmp_gt_i32_e64 s[0:1], s0, v2
	v_lshlrev_b32_e32 v44, 4, v2
	s_and_saveexec_b64 s[10:11], s[0:1]
	s_xor_b64 s[0:1], exec, s[10:11]
	s_mov_b32 s95, s4
	v_mov_b32_e32 v0, 3
	v_lshrrev_b32_sdwa v0, v0, v2 dst_sel:DWORD dst_unused:UNUSED_PAD src0_sel:DWORD src1_sel:BYTE_0
	v_and_b32_e32 v3, 0x70, v44
	s_movk_i32 s4, 0x90
	v_mad_u32_u24 v3, v0, s4, v3
	s_andn2_saveexec_b64 s[0:1], s[0:1]
	v_mov_b32_e32 v0, 2
	v_lshrrev_b32_sdwa v0, v0, v2 dst_sel:DWORD dst_unused:UNUSED_PAD src0_sel:DWORD src1_sel:BYTE_0
	v_mul_u32_u24_e32 v0, 0x50, v0
	v_and_b32_e32 v3, 48, v44
	s_movk_i32 s4, 0x1200
	v_add3_u32 v3, v0, v3, s4
	s_or_b64 exec, exec, s[0:1]
	s_add_i32 s30, 32, 0x14c00
	v_mov_b32_e32 v49, s30
	ds_read_b32 v49, v49
	v_cndmask_b32_e32 v0, v215, v234, vcc
	v_cndmask_b32_e32 v45, v235, v236, vcc
	v_lshl_add_u64 v[46:47], s[40:41], 0, v[0:1]
	s_lshl_b32 s36, s26, 18
	s_waitcnt lgkmcnt(0)
	v_readfirstlane_b32 s0, v49
	s_lshl_b32 s0, s0, 6
	v_lshlrev_b32_sdwa v0, v238, v2 dst_sel:DWORD dst_unused:UNUSED_PAD src0_sel:DWORD src1_sel:BYTE_0
	s_ashr_i32 s1, s0, 31
	v_lshl_add_u64 v[46:47], v[46:47], 0, s[36:37]
	v_cndmask_b32_e64 v48, v237, 48, vcc
	v_and_b32_e32 v0, v0, v45
	s_lshl_b64 s[10:11], s[0:1], 7
	s_or_b32 s0, s0, 32
	v_lshl_add_u64 v[46:47], v[46:47], 0, v[0:1]
	v_and_b32_e32 v0, v44, v48
	s_ashr_i32 s1, s0, 31
	v_lshl_add_u64 v[168:169], v[46:47], 0, v[0:1]
	s_lshl_b64 s[0:1], s[0:1], 7
	v_lshl_add_u64 v[44:45], v[168:169], 0, s[10:11]
	v_lshl_add_u64 v[48:49], v[168:169], 0, s[0:1]
	global_load_dwordx4 v[44:47], v[44:45], off
	v_add_u32_e32 v161, 32, v3
	global_load_dwordx4 v[108:111], v[48:49], off
	v_add_u32_e32 v172, 0x10000, v161
	v_bfe_u32 v205, v210, 3, 5
	v_bfe_u32 v206, v210, 4, 1
	v_bfe_u32 v207, v210, 6, 2
	v_lshl_or_b32 v206, v207, 1, v206
	v_and_b32_e32 v207, 7, v210
	v_xor_b32_e32 v206, v206, v207
	v_lshlrev_b32_e32 v206, 4, v206
	v_lshl_or_b32 v205, v205, 7, v206
	v_bfe_u32 v206, v210, 2, 6
	v_bfe_u32 v207, v210, 4, 2
	v_sub_u32_e32 v207, 0, v207
	v_and_b32_e32 v207, 3, v207
	v_and_b32_e32 v208, 3, v210
	v_xor_b32_e32 v207, v207, v208
	v_lshlrev_b32_e32 v207, 4, v207
	v_lshl_or_b32 v206, v206, 6, v207
	v_add_u32_e32 v206, 0x1000, v206
	v_bfe_u32 v207, v210, 8, 1
	v_cmp_ne_u32_e64 s[58:59], 0, v207
	s_nop 1
	v_cndmask_b32_e64 v205, v205, v206, s[58:59]
	v_add_u32_e32 v161, 32, v205
	v_add_u32_e32 v172, 0x10000, v161
	s_cmp_eq_u32 s8, 0
	s_waitcnt vmcnt(1)
	ds_write_b128 v172, v[44:47]
	s_waitcnt lgkmcnt(0)
	s_barrier
	s_cbranch_scc1 .LBB0_746
	s_bcnt1_i32_b32 s0, s8
	v_and_b32_e32 v0, 15, v2
	v_bfe_u32 v3, v2, 4, 2
	v_lshlrev_b32_e32 v44, 1, v2
	v_and_b32_e32 v2, 3, v2
	s_lshl_b32 s36, s0, 1
	v_and_or_b32 v2, v44, 24, v2
	v_lshlrev_b32_e32 v44, 4, v3
	v_readlane_b32 s0, v254, 59
	v_cmp_lt_f32_e64 s[8:9], s25, v155
	v_add_u32_e32 v45, s35, v44
	v_add_u32_e32 v47, s0, v44
	v_readlane_b32 s0, v254, 60
	v_mul_u32_u24_e32 v46, 0x90, v2
	v_mul_u32_u24_e32 v48, 0x50, v0
	v_add_u32_e32 v49, s0, v44
	v_readlane_b32 s0, v254, 61
	v_lshlrev_b32_e32 v173, 3, v3
	v_mov_b32_e32 v2, v1
	v_add_u32_e32 v44, s0, v44
	v_mov_b32_e32 v3, v1
	v_cndmask_b32_e64 v180, v155, v232, s[8:9]
	v_mov_b32_e32 v0, v1
	v_mov_b32_e32 v164, 0
	v_add_u32_e32 v176, v45, v46
	v_add_u32_e32 v177, v47, v48
	v_add_u32_e32 v178, v49, v46
	v_add_u32_e32 v179, v44, v48
	v_and_b32_e32 v205, 15, v228
	v_lshrrev_b32_e32 v206, 4, v228
	v_bfe_u32 v207, v205, 2, 2
	v_and_b32_e32 v208, 3, v205
	v_lshl_or_b32 v208, v207, 3, v208
	v_bfe_u32 v209, v205, 1, 1
	v_lshl_or_b32 v209, v207, 1, v209
	v_and_b32_e32 v217, 3, v209
	v_xor_b32_e32 v217, v206, v217
	v_lshrrev_b32_e32 v227, 2, v209
	v_lshlrev_b32_e32 v217, 4, v217
	v_lshl_or_b32 v217, v227, 6, v217
	v_lshl_or_b32 v208, v208, 7, v217
	v_xor_b32_e32 v217, 64, v208
	v_sub_u32_e32 v209, 0, v207
	v_and_b32_e32 v209, 3, v209
	v_xor_b32_e32 v209, v206, v209
	v_lshlrev_b32_e32 v209, 4, v209
	v_lshl_or_b32 v205, v205, 6, v209
	v_add_u32_e32 v205, 0x1000, v205
	v_add_u32_e32 v176, 0x10020, v208
	v_add_u32_e32 v230, 0x10020, v217
	v_add_u32_e32 v177, 0x10020, v205
	v_add_u32_e32 v178, 0x12620, v208
	v_add_u32_e32 v231, 0x12620, v217
	v_add_u32_e32 v179, 0x12620, v205
	v_mov_b64_e32 v[46:47], v[2:3]
	v_mov_b64_e32 v[50:51], v[2:3]
	v_mov_b64_e32 v[54:55], v[2:3]
	v_mov_b64_e32 v[58:59], v[2:3]
	v_mov_b64_e32 v[62:63], v[2:3]
	v_mov_b64_e32 v[66:67], v[2:3]
	v_mov_b64_e32 v[70:71], v[2:3]
	v_mov_b64_e32 v[74:75], v[2:3]
	v_mov_b64_e32 v[78:79], v[2:3]
	v_mov_b64_e32 v[82:83], v[2:3]
	v_mov_b64_e32 v[86:87], v[2:3]
	v_mov_b64_e32 v[90:91], v[2:3]
	v_mov_b64_e32 v[94:95], v[2:3]
	v_mov_b64_e32 v[98:99], v[2:3]
	v_mov_b64_e32 v[102:103], v[2:3]
	v_mov_b64_e32 v[106:107], v[2:3]
	s_add_i32 s43, s36, -2
	s_mov_b32 s54, 3
	s_add_i32 s55, s36, -1
	v_or_b32_e32 v174, 32, v173
	s_add_i32 s56, 32, 0x14c00
	v_lshlrev_b32_e32 v217, 2, v228
	v_add_u32_e32 v217, 0x14c20, v217
	ds_read_b32 v216, v217
	s_waitcnt lgkmcnt(0)
	v_mov_b64_e32 v[44:45], v[0:1]
	v_mov_b64_e32 v[48:49], v[0:1]
	v_mov_b64_e32 v[52:53], v[0:1]
	v_mov_b64_e32 v[56:57], v[0:1]
	v_mov_b64_e32 v[60:61], v[0:1]
	v_mov_b64_e32 v[64:65], v[0:1]
	v_mov_b64_e32 v[68:69], v[0:1]
	v_mov_b64_e32 v[72:73], v[0:1]
	v_mov_b64_e32 v[76:77], v[0:1]
	v_mov_b64_e32 v[80:81], v[0:1]
	v_mov_b64_e32 v[84:85], v[0:1]
	v_mov_b64_e32 v[88:89], v[0:1]
	v_mov_b64_e32 v[92:93], v[0:1]
	v_mov_b64_e32 v[96:97], v[0:1]
	v_mov_b64_e32 v[100:101], v[0:1]
	v_mov_b64_e32 v[104:105], v[0:1]
	v_mov_b32_e32 v0, v180
	v_mov_b32_e32 v2, v180
	v_mov_b32_e32 v3, v180
	v_mov_b32_e32 v165, v164
	v_mov_b32_e32 v166, v164
	v_mov_b32_e32 v167, v164
	s_branch .LBB0_727

; template <int MODE>
; DI void nsa_chunk(const KVFrag& f, int kb, int t, bool selbit, const bf16x8 (&qf)[4][2], f32x4 (&O)[4][4], float (&m)[4], float (&l)[4], int quad, bool online) {
;   const float SC = 0.125f * 1.44269504089f;
;   bool val[8];
; #pragma unroll
;   for (int idx = 0; idx < 8; ++idx) {
;     const int key = kb + 8 * quad + idx;
;     val[idx] = MODE == 0 ? (selbit && key <= t) : (key <= t && key > t - 512);
;   }
; template <int MODE>
; DI void nsa_branch(const bf16_t* __restrict__ Kb, const bf16_t* __restrict__ Vtb, unsigned char* lds, int nb, int t, int cur, unsigned selmask, unsigned umall,
;                    const bf16x8 (&qf)[4][2], f32x4 (&O)[4][4], float (&m)[4], float (&l)[4], bool online) {
;     ...
;   for (int n = 0; n < N; n += 2) {
;     const int j = blist[n >> 1];
;     const bool won = MODE == 0 ? ((umall >> j) & 1u) != 0 : (j >= cur - 8 && j <= cur);
;     const bool bit = (selmask >> j) & 1u;
;     ra = *(const u32x4*)(gsrc + (long)kbof(min(n + 2, N - 2)) * gmul);
;     if (won) { KVFrag f; nsa_ldsfrag(f, slot0, qi, quad); nsa_chunk<MODE>(f, j * 64, t, bit, qf, O, m, l, quad, online); }
.LBB0_727:
	s_sub_u32 s58, s56, 0x14c20
	s_lshr_b32 s58, s58, 2
	v_readlane_b32 s0, v216, s58
	s_nop 1
	v_mov_b32_e32 v181, s0
	s_lshl_b32 s10, 1, s0
	s_and_b32 s11, s10, s42
	s_cmp_lg_u32 s11, 0
	s_cselect_b64 s[0:1], -1, 0
	s_add_i32 s57, s54, -1
	s_min_i32 s12, s57, s43
	s_lshr_b32 s12, s12, 1
	v_readlane_b32 s58, v216, s12
	v_and_b32_e32 v116, s10, v171
	v_cmp_ne_u32_e64 s[12:13], 0, v116
	v_cndmask_b32_e64 v116, 0, 1, s[8:9]
	s_lshl_b32 s58, s58, 6
	s_ashr_i32 s59, s58, 31
	s_lshl_b64 s[58:59], s[58:59], 7
	s_cmp_eq_u32 s11, 0
	v_lshl_add_u64 v[112:113], v[168:169], 0, s[58:59]
	global_load_dwordx4 v[112:115], v[112:113], off
	v_cmp_ne_u32_e64 s[10:11], 1, v116
	s_cbranch_scc1 .LBB0_737
	s_and_b64 vcc, exec, s[10:11]
	s_cbranch_vccz .Lmy_nf_s1
	v_readfirstlane_b32 s58, v181
	v_readfirstlane_b32 s59, v160
	s_lshl_b32 s58, s58, 6
	s_add_u32 s60, s58, 63
	s_cmp_le_i32 s60, s59
	s_cbranch_scc0 .Lmy_nf_s1
	ds_read_b128 v[136:139], v176
	ds_read_b128 v[140:143], v230
	ds_read_b128 v[144:147], v176 offset:512
	ds_read_b128 v[132:135], v230 offset:512
	ds_read_b128 v[128:131], v177
	ds_read_b128 v[124:127], v177 offset:1024
	ds_read_b128 v[120:123], v177 offset:2048
	ds_read_b128 v[116:119], v177 offset:3072
	v_mov_b32_e32 v226, 0xff800000
	v_cndmask_b32_e64 v218, v226, 0, s[12:13]
	v_cndmask_b32_e64 v219, v226, 0, s[12:13]
	v_cndmask_b32_e64 v220, v226, 0, s[12:13]
	v_cndmask_b32_e64 v221, v226, 0, s[12:13]
	s_branch .Lmy_full_s1
.Lmy_nf_s1:
	v_lshl_or_b32 v182, v181, 6, v173
	v_cmp_le_i32_e32 vcc, v182, v160
	s_and_b64 s[16:17], s[12:13], vcc
	v_cmp_lt_i32_e32 vcc, v182, v160
	v_or_b32_e32 v148, 2, v182
	s_and_b64 s[18:19], s[12:13], vcc
	v_cmp_le_i32_e32 vcc, v148, v160
	v_or_b32_e32 v148, 3, v182
	s_and_b64 s[44:45], s[12:13], vcc
	v_cmp_le_i32_e32 vcc, v148, v160
	v_or_b32_e32 v148, 4, v182
	ds_read_b128 v[136:139], v176
	ds_read_b128 v[140:143], v230
	ds_read_b128 v[144:147], v176 offset:512
	ds_read_b128 v[132:135], v230 offset:512
	ds_read_b128 v[128:131], v177
	ds_read_b128 v[124:127], v177 offset:1024
	ds_read_b128 v[120:123], v177 offset:2048
	ds_read_b128 v[116:119], v177 offset:3072
	s_and_b64 s[46:47], s[12:13], vcc
	v_cmp_le_i32_e32 vcc, v148, v160
	v_or_b32_e32 v152, 5, v182
	s_and_b64 s[14:15], s[12:13], vcc
	v_cmp_le_i32_e32 vcc, v152, v160
	v_or_b32_e32 v183, 6, v182
	s_and_b64 s[48:49], s[12:13], vcc
	v_cmp_le_i32_e32 vcc, v183, v160
	v_or_b32_e32 v182, 7, v182
	s_and_b64 s[50:51], s[12:13], vcc
	v_cmp_le_i32_e32 vcc, v182, v160
	s_and_b64 s[52:53], s[12:13], vcc
	s_and_b64 vcc, exec, s[10:11]
	v_mov_b32_e32 v226, 0xff800000
	v_cndmask_b32_e64 v218, v226, 0, s[16:17]
	v_cndmask_b32_e64 v219, v226, 0, s[18:19]
	v_cndmask_b32_e64 v220, v226, 0, s[44:45]
	v_cndmask_b32_e64 v221, v226, 0, s[46:47]
	v_cndmask_b32_e64 v222, v226, 0, s[14:15]
	v_cndmask_b32_e64 v223, v226, 0, s[48:49]
	v_cndmask_b32_e64 v224, v226, 0, s[50:51]
	v_cndmask_b32_e64 v225, v226, 0, s[52:53]
	s_nop 1
	s_cbranch_vccnz .Lmy_fast_s1
	s_waitcnt lgkmcnt(7)
	v_mfma_f32_16x16x32_bf16 v[148:151], v[136:139], v[8:11], v[218:221]
	s_waitcnt lgkmcnt(6)
	v_mfma_f32_16x16x32_bf16 v[152:155], v[140:143], v[12:15], v[148:151]
	s_waitcnt lgkmcnt(5)
	v_mfma_f32_16x16x32_bf16 v[148:151], v[144:147], v[8:11], v[222:225]
	s_waitcnt lgkmcnt(4)
	v_mfma_f32_16x16x32_bf16 v[148:151], v[132:135], v[12:15], v[148:151]
	s_nop 7
	s_cbranch_vccnz .LBB0_730
	v_mul_f32_e32 v182, 0x3e38aa3b, v152
	v_max_f32_e32 v182, 0xf149f2ca, v182
	v_cndmask_b32_e64 v182, v232, v182, s[16:17]
	v_mul_f32_e32 v183, 0x3e38aa3b, v153
	v_max_f32_e32 v183, v182, v183
	v_cndmask_b32_e64 v182, v182, v183, s[18:19]
	v_mul_f32_e32 v183, 0x3e38aa3b, v154
	v_max_f32_e32 v183, v182, v183
	v_cndmask_b32_e64 v182, v182, v183, s[44:45]
	v_mul_f32_e32 v183, 0x3e38aa3b, v155
	v_max_f32_e32 v183, v182, v183
	v_cndmask_b32_e64 v182, v182, v183, s[46:47]
	v_mul_f32_e32 v183, 0x3e38aa3b, v148
	v_max_f32_e32 v183, v182, v183
	v_cndmask_b32_e64 v182, v182, v183, s[14:15]
	v_mul_f32_e32 v183, 0x3e38aa3b, v149
	v_max_f32_e32 v184, v182, v182
	v_max_f32_e32 v183, v184, v183
	v_cndmask_b32_e64 v182, v182, v183, s[48:49]
	v_mul_f32_e32 v183, 0x3e38aa3b, v150
	v_max_f32_e32 v184, v182, v182
	v_max_f32_e32 v183, v184, v183
	v_cndmask_b32_e64 v182, v182, v183, s[50:51]
	v_mul_f32_e32 v183, 0x3e38aa3b, v151
	v_max_f32_e32 v184, v182, v182
	v_max_f32_e32 v183, v184, v183
	v_cndmask_b32_e64 v182, v182, v183, s[52:53]
	ds_bpermute_b32 v183, v175, v182
	v_max_f32_e32 v182, v182, v182
	s_waitcnt lgkmcnt(0)
	v_max_f32_e32 v183, v183, v183
	v_max_f32_e32 v182, v182, v183
	ds_bpermute_b32 v183, v159, v182
	s_waitcnt lgkmcnt(0)
	v_max3_f32 v183, v3, v182, v183
	v_sub_f32_e32 v3, v3, v183
	v_exp_f32_e32 v182, v3
	v_mov_b32_e32 v3, v183
	v_mul_f32_e32 v167, v167, v182
	v_pk_mul_f32 v[106:107], v[106:107], v[182:183] op_sel_hi:[1,0]
	v_pk_mul_f32 v[104:105], v[104:105], v[182:183] op_sel_hi:[1,0]
	v_pk_mul_f32 v[102:103], v[102:103], v[182:183] op_sel_hi:[1,0]
	v_pk_mul_f32 v[100:101], v[100:101], v[182:183] op_sel_hi:[1,0]
	v_pk_mul_f32 v[98:99], v[98:99], v[182:183] op_sel_hi:[1,0]
	v_pk_mul_f32 v[96:97], v[96:97], v[182:183] op_sel_hi:[1,0]
	v_pk_mul_f32 v[94:95], v[94:95], v[182:183] op_sel_hi:[1,0]
	v_pk_mul_f32 v[92:93], v[92:93], v[182:183] op_sel_hi:[1,0]

; DI void nsa_ldsfrag(KVFrag& f, const unsigned char* slot, int qi, int quad) {
;   const int krow = 8 * (qi >> 2) + (qi & 3);
; #pragma unroll
;   for (int a = 0; a < 2; ++a) { const unsigned char* kp = slot + (krow + 4 * a) * NSA_KROW + quad * 16; f.k[a][0] = mk8(*(const u32x4*)kp); f.k[a][1] = mk8(*(const u32x4*)(kp + 64)); }
; #pragma unroll
;   for (int dt = 0; dt < 4; ++dt) f.v[dt] = mk8(*(const u32x4*)(slot + 32 * NSA_KROW + (dt * 16 + qi) * NSA_VROW + quad * 16));
; }
; template <int MODE>
; DI void nsa_branch(const bf16_t* __restrict__ Kb, const bf16_t* __restrict__ Vtb, unsigned char* lds, int nb, int t, int cur, unsigned selmask, unsigned umall,
;                    const bf16x8 (&qf)[4][2], f32x4 (&O)[4][4], float (&m)[4], float (&l)[4], bool online) {
;     ...
;     *(u32x4*)(slot1 + ldst) = rb;
;     __syncthreads();
;     rb = *(const u32x4*)(gsrc + (long)kbof(min(n + 3, N - 1)) * gmul);
;     if (won) { KVFrag f; nsa_ldsfrag(f, slot1, qi, quad); nsa_chunk<MODE>(f, j * 64 + 32, t, bit, qf, O, m, l, quad, online); }
.LBB0_737:
	s_min_i32 s14, s54, s55
	s_lshr_b32 s14, s14, 1
	v_add_u32_e32 v116, 0x12600, v161
	s_waitcnt vmcnt(1)
	ds_write_b128 v116, v[108:111]
	s_waitcnt lgkmcnt(0)
	s_barrier
	v_readlane_b32 s14, v216, s14
	s_andn2_b64 vcc, exec, s[0:1]
	s_lshl_b32 s14, s14, 6
	s_or_b32 s14, s14, 32
	s_ashr_i32 s15, s14, 31
	s_lshl_b64 s[14:15], s[14:15], 7
	v_lshl_add_u64 v[108:109], v[168:169], 0, s[14:15]
	global_load_dwordx4 v[108:111], v[108:109], off
	s_cbranch_vccnz .LBB0_726
	s_and_b64 vcc, exec, s[10:11]
	s_cbranch_vccz .Lmy_nf_s2
	v_readfirstlane_b32 s58, v181
	v_readfirstlane_b32 s59, v160
	s_lshl_b32 s58, s58, 6
	s_add_u32 s60, s58, 63
	s_cmp_le_i32 s60, s59
	s_cbranch_scc0 .Lmy_nf_s2
	ds_read_b128 v[136:139], v178
	ds_read_b128 v[140:143], v231
	ds_read_b128 v[144:147], v178 offset:512
	ds_read_b128 v[132:135], v231 offset:512
	ds_read_b128 v[128:131], v179
	ds_read_b128 v[124:127], v179 offset:1024
	ds_read_b128 v[120:123], v179 offset:2048
	ds_read_b128 v[116:119], v179 offset:3072
	v_mov_b32_e32 v226, 0xff800000
	v_cndmask_b32_e64 v218, v226, 0, s[12:13]
	v_cndmask_b32_e64 v219, v226, 0, s[12:13]
	v_cndmask_b32_e64 v220, v226, 0, s[12:13]
	v_cndmask_b32_e64 v221, v226, 0, s[12:13]
	s_branch .Lmy_full_s2
.Lmy_nf_s2:
	v_lshl_or_b32 v181, v181, 6, v174
	v_cmp_le_i32_e32 vcc, v181, v160
	s_and_b64 s[16:17], s[12:13], vcc
	v_cmp_lt_i32_e32 vcc, v181, v160
	v_or_b32_e32 v148, 2, v181
	s_and_b64 s[18:19], s[12:13], vcc
	v_cmp_le_i32_e32 vcc, v148, v160
	v_or_b32_e32 v148, 3, v181
	s_and_b64 s[44:45], s[12:13], vcc
	v_cmp_le_i32_e32 vcc, v148, v160
	v_or_b32_e32 v148, 4, v181
	ds_read_b128 v[136:139], v178
	ds_read_b128 v[140:143], v231
	ds_read_b128 v[144:147], v178 offset:512
	ds_read_b128 v[132:135], v231 offset:512
	ds_read_b128 v[128:131], v179
	ds_read_b128 v[124:127], v179 offset:1024
	ds_read_b128 v[120:123], v179 offset:2048
	ds_read_b128 v[116:119], v179 offset:3072
	s_and_b64 s[46:47], s[12:13], vcc
	v_cmp_le_i32_e32 vcc, v148, v160
	v_or_b32_e32 v152, 5, v181
	s_and_b64 s[14:15], s[12:13], vcc
	v_cmp_le_i32_e32 vcc, v152, v160
	v_or_b32_e32 v182, 6, v181
	s_and_b64 s[48:49], s[12:13], vcc
	v_cmp_le_i32_e32 vcc, v182, v160
	v_or_b32_e32 v181, 7, v181
	s_and_b64 s[50:51], s[12:13], vcc
	v_cmp_le_i32_e32 vcc, v181, v160
	s_and_b64 s[12:13], s[12:13], vcc
	s_and_b64 vcc, exec, s[10:11]
	v_mov_b32_e32 v226, 0xff800000
	v_cndmask_b32_e64 v218, v226, 0, s[16:17]
	v_cndmask_b32_e64 v219, v226, 0, s[18:19]
	v_cndmask_b32_e64 v220, v226, 0, s[44:45]
	v_cndmask_b32_e64 v221, v226, 0, s[46:47]
	v_cndmask_b32_e64 v222, v226, 0, s[14:15]
	v_cndmask_b32_e64 v223, v226, 0, s[48:49]
	v_cndmask_b32_e64 v224, v226, 0, s[50:51]
	v_cndmask_b32_e64 v225, v226, 0, s[12:13]
	s_nop 1
	s_cbranch_vccnz .Lmy_fast_s2
	s_waitcnt lgkmcnt(7)
	v_mfma_f32_16x16x32_bf16 v[148:151], v[136:139], v[8:11], v[218:221]
	s_waitcnt lgkmcnt(6)
	v_mfma_f32_16x16x32_bf16 v[152:155], v[140:143], v[12:15], v[148:151]
	s_waitcnt lgkmcnt(5)
	v_mfma_f32_16x16x32_bf16 v[148:151], v[144:147], v[8:11], v[222:225]
	s_waitcnt lgkmcnt(4)
	v_mfma_f32_16x16x32_bf16 v[148:151], v[132:135], v[12:15], v[148:151]
	s_nop 7
	s_cbranch_vccnz .LBB0_740
	v_mul_f32_e32 v181, 0x3e38aa3b, v152
	v_max_f32_e32 v181, 0xf149f2ca, v181
	v_cndmask_b32_e64 v181, v232, v181, s[16:17]
	v_mul_f32_e32 v182, 0x3e38aa3b, v153
	v_max_f32_e32 v182, v181, v182
	v_cndmask_b32_e64 v181, v181, v182, s[18:19]
	v_mul_f32_e32 v182, 0x3e38aa3b, v154
	v_max_f32_e32 v182, v181, v182
	v_cndmask_b32_e64 v181, v181, v182, s[44:45]
	v_mul_f32_e32 v182, 0x3e38aa3b, v155
	v_max_f32_e32 v182, v181, v182
	v_cndmask_b32_e64 v181, v181, v182, s[46:47]
	v_mul_f32_e32 v182, 0x3e38aa3b, v148
	v_max_f32_e32 v182, v181, v182
	v_cndmask_b32_e64 v181, v181, v182, s[14:15]
	v_mul_f32_e32 v182, 0x3e38aa3b, v149
	v_max_f32_e32 v183, v181, v181
	v_max_f32_e32 v182, v183, v182
	v_cndmask_b32_e64 v181, v181, v182, s[48:49]
	v_mul_f32_e32 v182, 0x3e38aa3b, v150
	v_max_f32_e32 v183, v181, v181
	v_max_f32_e32 v182, v183, v182
	v_cndmask_b32_e64 v181, v181, v182, s[50:51]
	v_mul_f32_e32 v182, 0x3e38aa3b, v151
	v_max_f32_e32 v183, v181, v181
	v_max_f32_e32 v182, v183, v182
	v_cndmask_b32_e64 v181, v181, v182, s[12:13]
	ds_bpermute_b32 v182, v175, v181
	v_max_f32_e32 v181, v181, v181
	s_waitcnt lgkmcnt(0)
	v_max_f32_e32 v182, v182, v182
	v_max_f32_e32 v181, v181, v182
	ds_bpermute_b32 v182, v159, v181
	s_waitcnt lgkmcnt(0)
	v_max3_f32 v181, v3, v181, v182
	v_sub_f32_e32 v3, v3, v181
	v_exp_f32_e32 v182, v3
	v_mov_b32_e32 v3, v181
	v_mul_f32_e32 v167, v167, v182
	v_pk_mul_f32 v[106:107], v[106:107], v[182:183] op_sel_hi:[1,0]
	v_pk_mul_f32 v[104:105], v[104:105], v[182:183] op_sel_hi:[1,0]
	v_pk_mul_f32 v[102:103], v[102:103], v[182:183] op_sel_hi:[1,0]
	v_pk_mul_f32 v[100:101], v[100:101], v[182:183] op_sel_hi:[1,0]
	v_pk_mul_f32 v[98:99], v[98:99], v[182:183] op_sel_hi:[1,0]
	v_pk_mul_f32 v[96:97], v[96:97], v[182:183] op_sel_hi:[1,0]
	v_pk_mul_f32 v[94:95], v[94:95], v[182:183] op_sel_hi:[1,0]
	v_pk_mul_f32 v[92:93], v[92:93], v[182:183] op_sel_hi:[1,0]

; DI int my_tid() { int t = threadIdx.x; asm volatile("" : "+v"(t)); return t; }
; template <int MODE>
; DI void nsa_branch(const bf16_t* __restrict__ Kb, const bf16_t* __restrict__ Vtb, unsigned char* lds, int nb, int t, int cur, unsigned selmask, unsigned umall,
;                    const bf16x8 (&qf)[4][2], f32x4 (&O)[4][4], float (&m)[4], float (&l)[4], bool online) {
;   const int tid = my_tid(), lane = tid & 63, qi = lane & 15, quad = lane >> 4;
;   const int* blist = (const int*)(lds + NSA_BLIST);
;   const bool isv = tid >= 256;
;   const int t2 = tid & 255;
;   const bf16_t* gsrc = isv ? Vtb + (t2 >> 2) * 32 + (t2 & 3) * 8 : Kb + (long)(t2 >> 3) * 64 + (t2 & 7) * 8;
;   const long gmul = 64;
;   const int ldst = isv ? 32 * NSA_KROW + (t2 >> 2) * NSA_VROW + (t2 & 3) * 16 : (t2 >> 3) * NSA_KROW + (t2 & 7) * 16;
;   unsigned char* slot0 = lds + NSA_SLOT0; unsigned char* slot1 = slot0 + NSA_SLOT;
;   const int N = 2 * nb;
;   auto kbof = [&](int n) { return blist[n >> 1] * 64 + (n & 1) * 32; };
;   u32x4 ra = *(const u32x4*)(gsrc + (long)kbof(0) * gmul), rb = *(const u32x4*)(gsrc + (long)kbof(1) * gmul);
;   *(u32x4*)(slot0 + ldst) = ra;
;   __syncthreads();
; DI void nsa_wave(const Params& p, int layer, int b, int g, int t0, unsigned char* lds, bf16_t* ybase) {
;     ...
;   {
;     const int cur0 = (t0 >> 7) * 2, jlo = cur0 >= 8 ? cur0 - 8 : 0;
;     nb = cur0 + 2 - jlo;
;     if (my_tid() < nb) blist[my_tid()] = jlo + my_tid();
;     __syncthreads();
;     nsa_branch<1>(p.kw() + (long)bg * SEQ * 64, p.vwt() + (long)bg * 64 * SEQ, lds, nb, t, cur, selmask, umall, qf, O, m, l, on_w);
.LBB0_749:
	s_or_b64 exec, exec, s[0:1]
	v_mov_b32_e32 v109, v210
	s_movk_i32 s0, 0xff
	s_waitcnt lgkmcnt(0)
	s_barrier
	s_nop 0
	v_cmp_lt_i32_e32 vcc, s0, v109
	s_movk_i32 s0, 0x100
	v_cmp_gt_i32_e64 s[0:1], s0, v109
	v_lshlrev_b32_e32 v3, 4, v109
	s_and_saveexec_b64 s[10:11], s[0:1]
	s_xor_b64 s[0:1], exec, s[10:11]
	v_mov_b32_e32 v0, 3
	v_lshrrev_b32_sdwa v0, v0, v109 dst_sel:DWORD dst_unused:UNUSED_PAD src0_sel:DWORD src1_sel:BYTE_0
	v_and_b32_e32 v2, 0x70, v3
	s_movk_i32 s4, 0x90
	v_mad_u32_u24 v2, v0, s4, v2
	s_andn2_saveexec_b64 s[0:1], s[0:1]
	v_mov_b32_e32 v0, 2
	v_lshrrev_b32_sdwa v0, v0, v109 dst_sel:DWORD dst_unused:UNUSED_PAD src0_sel:DWORD src1_sel:BYTE_0
	v_mul_u32_u24_e32 v0, 0x50, v0
	v_and_b32_e32 v2, 48, v3
	s_movk_i32 s4, 0x1200
	v_add3_u32 v2, v0, v2, s4
	s_or_b64 exec, exec, s[0:1]
	v_mov_b32_e32 v44, s30
	ds_read_b32 v44, v44
	v_cndmask_b32_e32 v0, v252, v229, vcc
	v_cndmask_b32_e32 v42, v235, v236, vcc
	v_lshl_add_u64 v[40:41], s[40:41], 0, v[0:1]
	s_lshl_b32 s36, s8, 1
	v_lshlrev_b32_sdwa v0, v238, v109 dst_sel:DWORD dst_unused:UNUSED_PAD src0_sel:DWORD src1_sel:BYTE_0
	s_waitcnt lgkmcnt(0)
	v_readfirstlane_b32 s0, v44
	v_lshl_add_u64 v[40:41], v[40:41], 0, s[36:37]
	v_cndmask_b32_e64 v43, v237, 48, vcc
	v_and_b32_e32 v0, v0, v42
	s_lshl_b32 s0, s0, 6
	v_lshl_add_u64 v[40:41], v[40:41], 0, v[0:1]
	v_and_b32_e32 v0, v3, v43
	s_ashr_i32 s1, s0, 31
	v_lshl_add_u64 v[164:165], v[40:41], 0, v[0:1]
	s_lshl_b64 s[8:9], s[0:1], 7
	s_or_b32 s0, s0, 32
	v_lshl_add_u64 v[40:41], v[164:165], 0, s[8:9]
	s_ashr_i32 s1, s0, 31
	global_load_dwordx4 v[40:43], v[40:41], off
	s_lshl_b64 s[0:1], s[0:1], 7
	v_lshl_add_u64 v[44:45], v[164:165], 0, s[0:1]
	global_load_dwordx4 v[104:107], v[44:45], off
	v_add_u32_e32 v161, 32, v2
	v_mov_b32_e32 v2, v1
	v_mov_b32_e32 v3, v1
	v_add_u32_e32 v166, 0x10000, v161
	v_bfe_u32 v205, v210, 3, 5
	v_bfe_u32 v206, v210, 4, 1
	v_bfe_u32 v207, v210, 6, 2
	v_lshl_or_b32 v206, v207, 1, v206
	v_and_b32_e32 v207, 7, v210
	v_xor_b32_e32 v206, v206, v207
	v_lshlrev_b32_e32 v206, 4, v206
	v_lshl_or_b32 v205, v205, 7, v206
	v_bfe_u32 v206, v210, 2, 6
	v_bfe_u32 v207, v210, 4, 2
	v_sub_u32_e32 v207, 0, v207
	v_and_b32_e32 v207, 3, v207
	v_and_b32_e32 v208, 3, v210
	v_xor_b32_e32 v207, v207, v208
	v_lshlrev_b32_e32 v207, 4, v207
	v_lshl_or_b32 v206, v206, 6, v207
	v_add_u32_e32 v206, 0x1000, v206
	v_bfe_u32 v207, v210, 8, 1
	v_cmp_ne_u32_e64 s[58:59], 0, v207
	s_nop 1
	v_cndmask_b32_e64 v205, v205, v206, s[58:59]
	v_add_u32_e32 v161, 32, v205
	v_add_u32_e32 v166, 0x10000, v161
	v_mov_b32_e32 v155, 0
	v_mov_b32_e32 v0, v1
	v_mov_b64_e32 v[102:103], v[2:3]
	v_mov_b64_e32 v[98:99], v[2:3]
	v_mov_b64_e32 v[94:95], v[2:3]
	v_mov_b64_e32 v[90:91], v[2:3]
	v_mov_b64_e32 v[86:87], v[2:3]
	v_mov_b64_e32 v[82:83], v[2:3]
	v_mov_b64_e32 v[78:79], v[2:3]
	v_mov_b64_e32 v[74:75], v[2:3]
	v_mov_b64_e32 v[70:71], v[2:3]
	v_mov_b64_e32 v[66:67], v[2:3]
	v_mov_b64_e32 v[62:63], v[2:3]
	v_mov_b64_e32 v[58:59], v[2:3]
	v_mov_b64_e32 v[54:55], v[2:3]
	v_mov_b64_e32 v[50:51], v[2:3]
	v_mov_b64_e32 v[46:47], v[2:3]
	v_cmp_lt_i32_e32 vcc, 0, v108
	v_mov_b32_e32 v154, v155
	v_mov_b32_e32 v153, v155
	v_mov_b32_e32 v152, v155
	v_mov_b64_e32 v[100:101], v[0:1]
	v_mov_b64_e32 v[96:97], v[0:1]
	v_mov_b64_e32 v[92:93], v[0:1]
	v_mov_b64_e32 v[88:89], v[0:1]
	v_mov_b64_e32 v[84:85], v[0:1]
	v_mov_b64_e32 v[80:81], v[0:1]
	v_mov_b64_e32 v[76:77], v[0:1]
	v_mov_b64_e32 v[72:73], v[0:1]
	v_mov_b64_e32 v[68:69], v[0:1]
	v_mov_b64_e32 v[64:65], v[0:1]
	v_mov_b64_e32 v[60:61], v[0:1]
	v_mov_b64_e32 v[56:57], v[0:1]
	v_mov_b64_e32 v[52:53], v[0:1]
	v_mov_b64_e32 v[48:49], v[0:1]
	v_mov_b64_e32 v[44:45], v[0:1]
	s_waitcnt vmcnt(1)
	ds_write_b128 v166, v[40:43]
	v_mov_b64_e32 v[42:43], v[2:3]
	v_mov_b64_e32 v[40:41], v[0:1]
	s_waitcnt lgkmcnt(0)
	s_barrier
	s_and_saveexec_b64 s[42:43], vcc
	s_cbranch_execz .LBB0_705
	v_bfe_u32 v2, v109, 4, 2
	v_lshlrev_b32_e32 v3, 1, v109
	v_and_b32_e32 v40, 3, v109
	v_and_or_b32 v3, v3, 24, v40
	v_lshlrev_b32_e32 v40, 4, v2
	v_readlane_b32 s0, v254, 59
	v_and_b32_e32 v0, 15, v109
	v_cmp_lt_f32_e64 s[44:45], s25, v156
	v_add_u32_e32 v43, s0, v40
	v_readlane_b32 s0, v254, 60
	v_add_u32_e32 v41, s35, v40
	v_mul_u32_u24_e32 v42, 0x90, v3
	v_add_u32_e32 v45, s0, v40
	v_readlane_b32 s0, v254, 61
	v_mul_u32_u24_e32 v44, 0x50, v0
	v_lshlrev_b32_e32 v169, 3, v2
	v_add_u32_e32 v40, s0, v40
	v_mov_b32_e32 v2, v1
	v_mov_b32_e32 v3, v1
	v_lshlrev_b32_e32 v167, 1, v108
	v_cndmask_b32_e64 v179, v156, v232, s[44:45]
	v_mov_b32_e32 v0, v1
	v_mov_b32_e32 v152, 0
	v_add_u32_e32 v174, v41, v42
	v_add_u32_e32 v176, v43, v44
	v_add_u32_e32 v177, v45, v42
	v_add_u32_e32 v178, v40, v44
	v_and_b32_e32 v205, 15, v228
	v_lshrrev_b32_e32 v206, 4, v228
	v_bfe_u32 v207, v205, 2, 2
	v_and_b32_e32 v208, 3, v205
	v_lshl_or_b32 v208, v207, 3, v208
	v_bfe_u32 v209, v205, 1, 1
	v_lshl_or_b32 v209, v207, 1, v209
	v_and_b32_e32 v217, 3, v209
	v_xor_b32_e32 v217, v206, v217
	v_lshrrev_b32_e32 v227, 2, v209
	v_lshlrev_b32_e32 v217, 4, v217
	v_lshl_or_b32 v217, v227, 6, v217
	v_lshl_or_b32 v208, v208, 7, v217
	v_xor_b32_e32 v217, 64, v208
	v_sub_u32_e32 v209, 0, v207
	v_and_b32_e32 v209, 3, v209
	v_xor_b32_e32 v209, v206, v209
	v_lshlrev_b32_e32 v209, 4, v209
	v_lshl_or_b32 v205, v205, 6, v209
	v_add_u32_e32 v205, 0x1000, v205
	v_add_u32_e32 v174, 0x10020, v208
	v_add_u32_e32 v230, 0x10020, v217
	v_add_u32_e32 v176, 0x10020, v205
	v_add_u32_e32 v177, 0x12620, v208
	v_add_u32_e32 v231, 0x12620, v217
	v_add_u32_e32 v178, 0x12620, v205
	v_mov_b64_e32 v[42:43], v[2:3]
	v_mov_b64_e32 v[46:47], v[2:3]
	v_mov_b64_e32 v[50:51], v[2:3]
	v_mov_b64_e32 v[54:55], v[2:3]
	v_mov_b64_e32 v[58:59], v[2:3]
	v_mov_b64_e32 v[62:63], v[2:3]
	v_mov_b64_e32 v[66:67], v[2:3]
	v_mov_b64_e32 v[70:71], v[2:3]
	v_mov_b64_e32 v[74:75], v[2:3]
	v_mov_b64_e32 v[78:79], v[2:3]
	v_mov_b64_e32 v[82:83], v[2:3]
	v_mov_b64_e32 v[86:87], v[2:3]
	v_mov_b64_e32 v[90:91], v[2:3]
	v_mov_b64_e32 v[94:95], v[2:3]
	v_mov_b64_e32 v[98:99], v[2:3]
	v_mov_b64_e32 v[102:103], v[2:3]
	v_add_u32_e32 v156, -8, v170
	v_add_u32_e32 v168, -2, v167
	s_mov_b32 s28, 3
	v_add_u32_e32 v171, 0xfffffe00, v160
	v_add_u32_e32 v172, -1, v167
	v_or_b32_e32 v173, 32, v169
	s_mov_b64 s[52:53], 0
	v_mov_b64_e32 v[40:41], v[0:1]
	v_mov_b64_e32 v[44:45], v[0:1]
	v_mov_b64_e32 v[48:49], v[0:1]
	v_mov_b64_e32 v[52:53], v[0:1]
	v_mov_b64_e32 v[56:57], v[0:1]
	v_mov_b64_e32 v[60:61], v[0:1]
	v_mov_b64_e32 v[64:65], v[0:1]
	v_mov_b64_e32 v[68:69], v[0:1]
	v_mov_b64_e32 v[72:73], v[0:1]
	v_mov_b64_e32 v[76:77], v[0:1]
	v_mov_b64_e32 v[80:81], v[0:1]
	v_mov_b64_e32 v[84:85], v[0:1]
	v_mov_b64_e32 v[88:89], v[0:1]
	v_mov_b64_e32 v[92:93], v[0:1]
	v_mov_b64_e32 v[96:97], v[0:1]
	v_mov_b64_e32 v[100:101], v[0:1]
	v_mov_b32_e32 v0, v179
	v_mov_b32_e32 v2, v179
	v_mov_b32_e32 v3, v179
	v_mov_b32_e32 v153, v152
	v_mov_b32_e32 v154, v152
	v_mov_b32_e32 v155, v152
	s_branch .LBB0_757

; template <int MODE>
; DI void nsa_chunk(const KVFrag& f, int kb, int t, bool selbit, const bf16x8 (&qf)[4][2], f32x4 (&O)[4][4], float (&m)[4], float (&l)[4], int quad, bool online) {
;   const float SC = 0.125f * 1.44269504089f;
;   bool val[8];
; #pragma unroll
;   for (int idx = 0; idx < 8; ++idx) {
;     const int key = kb + 8 * quad + idx;
;     val[idx] = MODE == 0 ? (selbit && key <= t) : (key <= t && key > t - 512);
;   }
; template <int MODE>
; DI void nsa_branch(const bf16_t* __restrict__ Kb, const bf16_t* __restrict__ Vtb, unsigned char* lds, int nb, int t, int cur, unsigned selmask, unsigned umall,
;                    const bf16x8 (&qf)[4][2], f32x4 (&O)[4][4], float (&m)[4], float (&l)[4], bool online) {
;     ...
;   for (int n = 0; n < N; n += 2) {
;     const int j = blist[n >> 1];
;     const bool won = MODE == 0 ? ((umall >> j) & 1u) != 0 : (j >= cur - 8 && j <= cur);
;     const bool bit = (selmask >> j) & 1u;
;     ra = *(const u32x4*)(gsrc + (long)kbof(min(n + 2, N - 2)) * gmul);
;     if (won) { KVFrag f; nsa_ldsfrag(f, slot0, qi, quad); nsa_chunk<MODE>(f, j * 64, t, bit, qf, O, m, l, quad, online); }
.LBB0_757:
	v_mov_b32_e32 v108, s30
	s_add_i32 s36, s28, -1
	ds_read_b32 v180, v108
	v_min_i32_e32 v108, s36, v168
	v_lshl_add_u32 v108, v108, 1, 32
	v_add_u32_e32 v108, 0x14c00, v108
	ds_read_b32 v108, v108
	s_waitcnt lgkmcnt(1)
	v_cmp_ge_i32_e32 vcc, v180, v156
	v_cmp_le_i32_e64 s[0:1], v180, v170
	v_cndmask_b32_e64 v112, 0, 1, s[44:45]
	s_and_b64 s[54:55], vcc, s[0:1]
	s_waitcnt lgkmcnt(0)
	v_lshlrev_b32_e32 v108, 6, v108
	v_ashrrev_i32_e32 v109, 31, v108
	v_lshlrev_b64 v[108:109], 7, v[108:109]
	v_lshl_add_u64 v[108:109], v[164:165], 0, v[108:109]
	global_load_dwordx4 v[108:111], v[108:109], off
	v_cmp_ne_u32_e64 s[8:9], 1, v112
	s_and_saveexec_b64 s[56:57], s[54:55]
	s_cbranch_execz .LBB0_767
	s_and_b64 vcc, exec, s[8:9]
	s_cbranch_vccz .Lmy_nf_w1
	v_readfirstlane_b32 s58, v180
	v_readfirstlane_b32 s59, v160
	s_lshl_b32 s58, s58, 6
	s_add_u32 s60, s58, 63
	s_cmp_le_i32 s60, s59
	s_cbranch_scc0 .Lmy_nf_w1
	s_sub_u32 s60, s59, 0x1f1
	s_cmp_gt_i32 s58, s60
	s_cbranch_scc0 .Lmy_nf_w1
	ds_read_b128 v[132:135], v174
	ds_read_b128 v[136:139], v230
	ds_read_b128 v[140:143], v174 offset:512
	ds_read_b128 v[128:131], v230 offset:512
	ds_read_b128 v[124:127], v176
	ds_read_b128 v[120:123], v176 offset:1024
	ds_read_b128 v[116:119], v176 offset:2048
	ds_read_b128 v[112:115], v176 offset:3072
	s_branch .Lmy_full_w1
.Lmy_nf_w1:
	v_lshl_or_b32 v181, v180, 6, v169
	v_cmp_le_i32_e32 vcc, v181, v160
	v_cmp_gt_i32_e64 s[0:1], v181, v171
	s_and_b64 s[10:11], vcc, s[0:1]
	v_cmp_lt_i32_e32 vcc, v181, v160
	v_cmp_ge_i32_e64 s[0:1], v181, v171
	v_or_b32_e32 v144, 2, v181
	s_and_b64 s[14:15], vcc, s[0:1]
	v_cmp_le_i32_e32 vcc, v144, v160
	v_cmp_gt_i32_e64 s[0:1], v144, v171
	v_or_b32_e32 v144, 3, v181
	s_and_b64 s[18:19], vcc, s[0:1]
	v_cmp_le_i32_e32 vcc, v144, v160
	v_cmp_gt_i32_e64 s[0:1], v144, v171
	v_or_b32_e32 v144, 4, v181
	s_and_b64 s[46:47], vcc, s[0:1]
	v_cmp_le_i32_e32 vcc, v144, v160
	v_cmp_gt_i32_e64 s[0:1], v144, v171
	v_or_b32_e32 v144, 5, v181
	ds_read_b128 v[132:135], v174
	ds_read_b128 v[136:139], v230
	ds_read_b128 v[140:143], v174 offset:512
	ds_read_b128 v[128:131], v230 offset:512
	ds_read_b128 v[124:127], v176
	ds_read_b128 v[120:123], v176 offset:1024
	ds_read_b128 v[116:119], v176 offset:2048
	ds_read_b128 v[112:115], v176 offset:3072
	s_and_b64 s[12:13], vcc, s[0:1]
	v_cmp_le_i32_e32 vcc, v144, v160
	v_cmp_gt_i32_e64 s[0:1], v144, v171
	v_or_b32_e32 v148, 6, v181
	s_and_b64 s[16:17], vcc, s[0:1]
	v_cmp_le_i32_e32 vcc, v148, v160
	v_cmp_gt_i32_e64 s[0:1], v148, v171
	v_or_b32_e32 v181, 7, v181
	s_and_b64 s[48:49], vcc, s[0:1]
	v_cmp_le_i32_e32 vcc, v181, v160
	v_cmp_gt_i32_e64 s[0:1], v181, v171
	s_and_b64 s[50:51], vcc, s[0:1]
	s_and_b64 vcc, exec, s[8:9]
	v_mov_b32_e32 v226, 0xff800000
	v_cndmask_b32_e64 v218, v226, 0, s[10:11]
	v_cndmask_b32_e64 v219, v226, 0, s[14:15]
	v_cndmask_b32_e64 v220, v226, 0, s[18:19]
	v_cndmask_b32_e64 v221, v226, 0, s[46:47]
	v_cndmask_b32_e64 v222, v226, 0, s[12:13]
	v_cndmask_b32_e64 v223, v226, 0, s[16:17]
	v_cndmask_b32_e64 v224, v226, 0, s[48:49]
	v_cndmask_b32_e64 v225, v226, 0, s[50:51]
	s_nop 1
	s_cbranch_vccnz .Lmy_fast_w1
	s_waitcnt lgkmcnt(7)
	v_mfma_f32_16x16x32_bf16 v[144:147], v[132:135], v[8:11], v[218:221]
	s_waitcnt lgkmcnt(6)
	v_mfma_f32_16x16x32_bf16 v[148:151], v[136:139], v[12:15], v[144:147]
	s_waitcnt lgkmcnt(5)
	v_mfma_f32_16x16x32_bf16 v[144:147], v[140:143], v[8:11], v[222:225]
	s_waitcnt lgkmcnt(4)
	v_mfma_f32_16x16x32_bf16 v[144:147], v[128:131], v[12:15], v[144:147]
	s_nop 7
	s_cbranch_vccnz .LBB0_760
	v_mul_f32_e32 v181, 0x3e38aa3b, v148
	v_max_f32_e32 v181, 0xf149f2ca, v181
	v_cndmask_b32_e64 v181, v232, v181, s[10:11]
	v_mul_f32_e32 v182, 0x3e38aa3b, v149
	v_max_f32_e32 v182, v181, v182
	v_cndmask_b32_e64 v181, v181, v182, s[14:15]
	v_mul_f32_e32 v182, 0x3e38aa3b, v150
	v_max_f32_e32 v182, v181, v182
	v_cndmask_b32_e64 v181, v181, v182, s[18:19]
	v_mul_f32_e32 v182, 0x3e38aa3b, v151
	v_max_f32_e32 v182, v181, v182
	v_cndmask_b32_e64 v181, v181, v182, s[46:47]
	v_mul_f32_e32 v182, 0x3e38aa3b, v144
	v_max_f32_e32 v182, v181, v182
	v_cndmask_b32_e64 v181, v181, v182, s[12:13]
	v_mul_f32_e32 v182, 0x3e38aa3b, v145
	v_max_f32_e32 v183, v181, v181
	v_max_f32_e32 v182, v183, v182
	v_cndmask_b32_e64 v181, v181, v182, s[16:17]
	v_mul_f32_e32 v182, 0x3e38aa3b, v146
	v_max_f32_e32 v183, v181, v181
	v_max_f32_e32 v182, v183, v182
	v_cndmask_b32_e64 v181, v181, v182, s[48:49]
	v_mul_f32_e32 v182, 0x3e38aa3b, v147
	v_max_f32_e32 v183, v181, v181
	v_max_f32_e32 v182, v183, v182
	v_cndmask_b32_e64 v181, v181, v182, s[50:51]
	ds_bpermute_b32 v182, v175, v181
	v_max_f32_e32 v181, v181, v181
	s_waitcnt lgkmcnt(0)
	v_max_f32_e32 v182, v182, v182
	v_max_f32_e32 v181, v181, v182
	ds_bpermute_b32 v182, v159, v181
	s_waitcnt lgkmcnt(0)
	v_max3_f32 v181, v3, v181, v182
	v_sub_f32_e32 v3, v3, v181
	v_exp_f32_e32 v182, v3
	v_mov_b32_e32 v3, v181
	v_mul_f32_e32 v155, v155, v182
	v_pk_mul_f32 v[102:103], v[102:103], v[182:183] op_sel_hi:[1,0]
	v_pk_mul_f32 v[100:101], v[100:101], v[182:183] op_sel_hi:[1,0]
	v_pk_mul_f32 v[98:99], v[98:99], v[182:183] op_sel_hi:[1,0]
	v_pk_mul_f32 v[96:97], v[96:97], v[182:183] op_sel_hi:[1,0]
	v_pk_mul_f32 v[94:95], v[94:95], v[182:183] op_sel_hi:[1,0]
	v_pk_mul_f32 v[92:93], v[92:93], v[182:183] op_sel_hi:[1,0]
	v_pk_mul_f32 v[90:91], v[90:91], v[182:183] op_sel_hi:[1,0]
	v_pk_mul_f32 v[88:89], v[88:89], v[182:183] op_sel_hi:[1,0]

; DI void nsa_ldsfrag(KVFrag& f, const unsigned char* slot, int qi, int quad) {
;   const int krow = 8 * (qi >> 2) + (qi & 3);
; #pragma unroll
;   for (int a = 0; a < 2; ++a) { const unsigned char* kp = slot + (krow + 4 * a) * NSA_KROW + quad * 16; f.k[a][0] = mk8(*(const u32x4*)kp); f.k[a][1] = mk8(*(const u32x4*)(kp + 64)); }
; #pragma unroll
;   for (int dt = 0; dt < 4; ++dt) f.v[dt] = mk8(*(const u32x4*)(slot + 32 * NSA_KROW + (dt * 16 + qi) * NSA_VROW + quad * 16));
; }
; template <int MODE>
; DI void nsa_branch(const bf16_t* __restrict__ Kb, const bf16_t* __restrict__ Vtb, unsigned char* lds, int nb, int t, int cur, unsigned selmask, unsigned umall,
;                    const bf16x8 (&qf)[4][2], f32x4 (&O)[4][4], float (&m)[4], float (&l)[4], bool online) {
;     ...
;     *(u32x4*)(slot1 + ldst) = rb;
;     __syncthreads();
;     rb = *(const u32x4*)(gsrc + (long)kbof(min(n + 3, N - 1)) * gmul);
;     if (won) { KVFrag f; nsa_ldsfrag(f, slot1, qi, quad); nsa_chunk<MODE>(f, j * 64 + 32, t, bit, qf, O, m, l, quad, online); }
.LBB0_767:
	s_or_b64 exec, exec, s[56:57]
	v_add_u32_e32 v112, 0x12600, v161
	s_waitcnt vmcnt(1)
	ds_write_b128 v112, v[104:107]
	v_min_i32_e32 v104, s28, v172
	v_lshlrev_b32_e32 v104, 1, v104
	v_and_b32_e32 v104, -4, v104
	v_add_u32_e32 v104, 32, v104
	v_add_u32_e32 v104, 0x14c00, v104
	s_waitcnt lgkmcnt(0)
	s_barrier
	ds_read_b32 v104, v104
	s_waitcnt lgkmcnt(0)
	v_lshl_or_b32 v104, v104, 6, 32
	v_ashrrev_i32_e32 v105, 31, v104
	v_lshlrev_b64 v[104:105], 7, v[104:105]
	v_lshl_add_u64 v[104:105], v[164:165], 0, v[104:105]
	global_load_dwordx4 v[104:107], v[104:105], off
	s_and_saveexec_b64 s[56:57], s[54:55]
	s_cbranch_execz .LBB0_756
	s_and_b64 vcc, exec, s[8:9]
	s_cbranch_vccz .Lmy_nf_w2
	v_readfirstlane_b32 s58, v180
	v_readfirstlane_b32 s59, v160
	s_lshl_b32 s58, s58, 6
	s_add_u32 s60, s58, 63
	s_cmp_le_i32 s60, s59
	s_cbranch_scc0 .Lmy_nf_w2
	s_sub_u32 s60, s59, 0x1f1
	s_cmp_gt_i32 s58, s60
	s_cbranch_scc0 .Lmy_nf_w2
	ds_read_b128 v[132:135], v177
	ds_read_b128 v[136:139], v231
	ds_read_b128 v[140:143], v177 offset:512
	ds_read_b128 v[128:131], v231 offset:512
	ds_read_b128 v[124:127], v178
	ds_read_b128 v[120:123], v178 offset:1024
	ds_read_b128 v[116:119], v178 offset:2048
	ds_read_b128 v[112:115], v178 offset:3072
	s_branch .Lmy_full_w2
.Lmy_nf_w2:
	v_lshl_or_b32 v180, v180, 6, v173
	v_cmp_le_i32_e32 vcc, v180, v160
	v_cmp_gt_i32_e64 s[0:1], v180, v171
	s_and_b64 s[10:11], vcc, s[0:1]
	v_cmp_lt_i32_e32 vcc, v180, v160
	v_cmp_ge_i32_e64 s[0:1], v180, v171
	v_or_b32_e32 v144, 2, v180
	s_and_b64 s[14:15], vcc, s[0:1]
	v_cmp_le_i32_e32 vcc, v144, v160
	v_cmp_gt_i32_e64 s[0:1], v144, v171
	v_or_b32_e32 v144, 3, v180
	s_and_b64 s[18:19], vcc, s[0:1]
	v_cmp_le_i32_e32 vcc, v144, v160
	v_cmp_gt_i32_e64 s[0:1], v144, v171
	v_or_b32_e32 v144, 4, v180
	s_and_b64 s[46:47], vcc, s[0:1]
	v_cmp_le_i32_e32 vcc, v144, v160
	v_cmp_gt_i32_e64 s[0:1], v144, v171
	v_or_b32_e32 v144, 5, v180
	ds_read_b128 v[132:135], v177
	ds_read_b128 v[136:139], v231
	ds_read_b128 v[140:143], v177 offset:512
	ds_read_b128 v[128:131], v231 offset:512
	ds_read_b128 v[124:127], v178
	ds_read_b128 v[120:123], v178 offset:1024
	ds_read_b128 v[116:119], v178 offset:2048
	ds_read_b128 v[112:115], v178 offset:3072
	s_and_b64 s[12:13], vcc, s[0:1]
	v_cmp_le_i32_e32 vcc, v144, v160
	v_cmp_gt_i32_e64 s[0:1], v144, v171
	v_or_b32_e32 v148, 6, v180
	s_and_b64 s[16:17], vcc, s[0:1]
	v_cmp_le_i32_e32 vcc, v148, v160
	v_cmp_gt_i32_e64 s[0:1], v148, v171
	v_or_b32_e32 v180, 7, v180
	s_and_b64 s[48:49], vcc, s[0:1]
	v_cmp_le_i32_e32 vcc, v180, v160
	v_cmp_gt_i32_e64 s[0:1], v180, v171
	s_and_b64 s[50:51], vcc, s[0:1]
	s_and_b64 vcc, exec, s[8:9]
	v_mov_b32_e32 v226, 0xff800000
	v_cndmask_b32_e64 v218, v226, 0, s[10:11]
	v_cndmask_b32_e64 v219, v226, 0, s[14:15]
	v_cndmask_b32_e64 v220, v226, 0, s[18:19]
	v_cndmask_b32_e64 v221, v226, 0, s[46:47]
	v_cndmask_b32_e64 v222, v226, 0, s[12:13]
	v_cndmask_b32_e64 v223, v226, 0, s[16:17]
	v_cndmask_b32_e64 v224, v226, 0, s[48:49]
	v_cndmask_b32_e64 v225, v226, 0, s[50:51]
	s_nop 1
	s_cbranch_vccnz .Lmy_fast_w2
	s_waitcnt lgkmcnt(7)
	v_mfma_f32_16x16x32_bf16 v[144:147], v[132:135], v[8:11], v[218:221]
	s_waitcnt lgkmcnt(6)
	v_mfma_f32_16x16x32_bf16 v[148:151], v[136:139], v[12:15], v[144:147]
	s_waitcnt lgkmcnt(5)
	v_mfma_f32_16x16x32_bf16 v[144:147], v[140:143], v[8:11], v[222:225]
	s_waitcnt lgkmcnt(4)
	v_mfma_f32_16x16x32_bf16 v[144:147], v[128:131], v[12:15], v[144:147]
	s_nop 7
	s_cbranch_vccnz .LBB0_770
	v_mul_f32_e32 v180, 0x3e38aa3b, v148
	v_max_f32_e32 v180, 0xf149f2ca, v180
	v_cndmask_b32_e64 v180, v232, v180, s[10:11]
	v_mul_f32_e32 v181, 0x3e38aa3b, v149
	v_max_f32_e32 v181, v180, v181
	v_cndmask_b32_e64 v180, v180, v181, s[14:15]
	v_mul_f32_e32 v181, 0x3e38aa3b, v150
	v_max_f32_e32 v181, v180, v181
	v_cndmask_b32_e64 v180, v180, v181, s[18:19]
	v_mul_f32_e32 v181, 0x3e38aa3b, v151
	v_max_f32_e32 v181, v180, v181
	v_cndmask_b32_e64 v180, v180, v181, s[46:47]
	v_mul_f32_e32 v181, 0x3e38aa3b, v144
	v_max_f32_e32 v181, v180, v181
	v_cndmask_b32_e64 v180, v180, v181, s[12:13]
	v_mul_f32_e32 v181, 0x3e38aa3b, v145
	v_max_f32_e32 v182, v180, v180
	v_max_f32_e32 v181, v182, v181
	v_cndmask_b32_e64 v180, v180, v181, s[16:17]
	v_mul_f32_e32 v181, 0x3e38aa3b, v146
	v_max_f32_e32 v182, v180, v180
	v_max_f32_e32 v181, v182, v181
	v_cndmask_b32_e64 v180, v180, v181, s[48:49]
	v_mul_f32_e32 v181, 0x3e38aa3b, v147
	v_max_f32_e32 v182, v180, v180
	v_max_f32_e32 v181, v182, v181
	v_cndmask_b32_e64 v180, v180, v181, s[50:51]
	ds_bpermute_b32 v181, v175, v180
	v_max_f32_e32 v180, v180, v180
	s_waitcnt lgkmcnt(0)
	v_max_f32_e32 v181, v181, v181
	v_max_f32_e32 v180, v180, v181
	ds_bpermute_b32 v181, v159, v180
	s_waitcnt lgkmcnt(0)
	v_max3_f32 v181, v3, v180, v181
	v_sub_f32_e32 v3, v3, v181
	v_exp_f32_e32 v180, v3
	v_mov_b32_e32 v3, v181
	v_mul_f32_e32 v155, v155, v180
	v_pk_mul_f32 v[102:103], v[102:103], v[180:181] op_sel_hi:[1,0]
	v_pk_mul_f32 v[100:101], v[100:101], v[180:181] op_sel_hi:[1,0]
	v_pk_mul_f32 v[98:99], v[98:99], v[180:181] op_sel_hi:[1,0]
	v_pk_mul_f32 v[96:97], v[96:97], v[180:181] op_sel_hi:[1,0]
	v_pk_mul_f32 v[94:95], v[94:95], v[180:181] op_sel_hi:[1,0]
	v_pk_mul_f32 v[92:93], v[92:93], v[180:181] op_sel_hi:[1,0]
	v_pk_mul_f32 v[90:91], v[90:91], v[180:181] op_sel_hi:[1,0]
	v_pk_mul_f32 v[88:89], v[88:89], v[180:181] op_sel_hi:[1,0]
